# same as previous plus a grid-size guard: the one-sample-row-per-workgroup mapping in ROW_P1 only when the grid is 256 workgroups
# baseline (speedup 1.0000x reference)
; __device__ __forceinline__ unsigned char* WSP() { return (unsigned char*)IN(41); }
; __device__ __forceinline__ unsigned pk2(float lo, float hi) { f32x2c v = {lo, hi}; return __builtin_bit_cast(unsigned, __builtin_convertvector(v, bf16x2c)); }
; __device__ __forceinline__ void presum_sample_rows(bf16_t* MIX, int bid, int tid) {
;     if (bid < MS / 4) {
; #pragma unroll 1
;         for (int r = 0; r < 4; ++r) {
;             const size_t off = (size_t)(4 * bid + r) * D + 4 * tid;
;             const float* pb = (const float*)(WSP() + WS_PB) + off;
;             f32x4 v[KSPLIT];
; #pragma unroll
;             for (int k = 0; k < KSPLIT; ++k) v[k] = *(const f32x4*)(pb + (size_t)k * 256 * D);
; #pragma unroll
;             for (int k = 1; k < KSPLIT; ++k) v[0] += v[k];
;             { u32x2 w; w.x = pk2(v[0][0], v[0][1]); w.y = pk2(v[0][2], v[0][3]); *(u32x2*)(MIX + (size_t)MP * D + off) = w; }
;         }
;     }
;     __syncthreads();
; }
.LBB0_978:
	s_andn2_b64 vcc, exec, s[2:3]
	s_cbranch_vccnz .LBB0_1238
	s_cmp_lt_i32 s37, 8
	s_mov_b64 s[2:3], -1
	s_cbranch_scc1 .LBB0_1011
	s_cmp_gt_i32 s37, 8
	s_cbranch_scc0 .LBB0_998
	v_mov_b32_e32 v0, v146
	s_mov_b32 s14, s67
	s_load_dwordx2 s[2:3], s[0:1], 0x150
	s_movk_i32 s8, 0x48
	v_readfirstlane_b32 s4, v0
	v_lshlrev_b32_e32 v0, 2, v0
	s_waitcnt lgkmcnt(0)
	s_mov_b32 s5, s2
	s_movk_i32 s2, 0x148
	s_ashr_i32 s3, s2, 31
	s_add_u32 s2, s0, s2
	s_addc_u32 s3, s1, s3
	s_load_dwordx2 s[6:7], s[2:3], 0x0
	s_mov_b32 s2, 64
	s_ashr_i32 s3, s2, 31
	s_add_u32 s2, s0, s2
	s_addc_u32 s3, s1, s3
	s_load_dwordx2 s[2:3], s[2:3], 0x0
	s_ashr_i32 s9, s8, 31
	s_add_u32 s8, s0, s8
	s_addc_u32 s9, s1, s9
	s_load_dwordx2 s[10:11], s[8:9], 0x0
	s_cmp_eq_u32 s5, 0x100
	s_cselect_b32 s100, 0, 2
	s_cselect_b32 s101, 0x100, 64
	s_cmp_lt_i32 s14, s101
	s_cselect_b64 s[8:9], -1, 0
	s_cmp_ge_i32 s14, s101
	s_cbranch_scc1 .LBB0_984
	s_lshl_b32 s12, s14, s100
	s_movk_i32 s98, 0x2000
	s_lshl_b32 s98, s98, s100
	s_ashr_i32 s13, s12, 31
	s_lshl_b64 s[16:17], s[12:13], 12
	s_waitcnt lgkmcnt(0)
	s_add_u32 s16, s6, s16
	v_ashrrev_i32_e32 v1, 31, v0
	s_addc_u32 s17, s7, s17
	s_waitcnt vmcnt(0)
	v_lshl_add_u64 v[4:5], v[0:1], 1, s[16:17]
	s_mov_b64 s[16:17], 0x12d00000
	s_lshl_b64 s[12:13], s[12:13], 13
	v_lshl_add_u64 v[4:5], v[4:5], 0, s[16:17]
	v_lshl_add_u64 v[6:7], v[0:1], 2, s[12:13]
	s_mov_b64 s[12:13], 0
.LBB0_983:
	s_movk_i32 s15, 0x148
	s_ashr_i32 s17, s15, 31
	s_add_u32 s16, s0, s15
	s_addc_u32 s17, s1, s17
	s_load_dwordx2 s[16:17], s[16:17], 0x0
	s_waitcnt lgkmcnt(0)
	v_lshl_add_u64 v[8:9], s[16:17], 0, v[6:7]
	s_waitcnt vmcnt(0)
	v_lshl_add_u64 v[68:69], v[8:9], 0, s[12:13]
	v_add_co_u32_e32 v8, vcc, 0x33e00000, v68
	s_add_u32 s12, s12, 0x2000
	s_nop 0
	v_addc_co_u32_e32 v9, vcc, 0, v69, vcc
	v_add_co_u32_e32 v12, vcc, 0x34000000, v68
	s_addc_u32 s13, s13, 0
	s_nop 0
	v_addc_co_u32_e32 v13, vcc, 0, v69, vcc
	v_add_co_u32_e32 v16, vcc, 0x34200000, v68
	global_load_dwordx4 v[8:11], v[8:9], off
	s_nop 0
	global_load_dwordx4 v[12:15], v[12:13], off
	v_addc_co_u32_e32 v17, vcc, 0, v69, vcc
	v_add_co_u32_e32 v20, vcc, 0x34400000, v68
	s_cmp_lg_u32 s12, s98
	s_nop 0
	v_addc_co_u32_e32 v21, vcc, 0, v69, vcc
	v_add_co_u32_e32 v24, vcc, 0x34600000, v68
	global_load_dwordx4 v[16:19], v[16:17], off
	s_nop 0
	global_load_dwordx4 v[20:23], v[20:21], off
	v_addc_co_u32_e32 v25, vcc, 0, v69, vcc
	v_add_co_u32_e32 v28, vcc, 0x34800000, v68
	s_waitcnt vmcnt(2)
	v_pk_add_f32 v[10:11], v[10:11], v[14:15]
	v_addc_co_u32_e32 v29, vcc, 0, v69, vcc
	v_add_co_u32_e32 v32, vcc, 0x34a00000, v68
	global_load_dwordx4 v[24:27], v[24:25], off
	s_nop 0
	global_load_dwordx4 v[28:31], v[28:29], off
	v_addc_co_u32_e32 v33, vcc, 0, v69, vcc
	v_add_co_u32_e32 v36, vcc, 0x34c00000, v68
	v_pk_add_f32 v[8:9], v[8:9], v[12:13]
	s_nop 0
	v_addc_co_u32_e32 v37, vcc, 0, v69, vcc
	v_add_co_u32_e32 v40, vcc, 0x34e00000, v68
	global_load_dwordx4 v[32:35], v[32:33], off
	s_nop 0
	global_load_dwordx4 v[36:39], v[36:37], off
	v_addc_co_u32_e32 v41, vcc, 0, v69, vcc
	v_add_co_u32_e32 v44, vcc, 0x35000000, v68
	s_waitcnt vmcnt(5)
	v_pk_add_f32 v[10:11], v[18:19], v[10:11]
	v_addc_co_u32_e32 v45, vcc, 0, v69, vcc
	v_add_co_u32_e32 v48, vcc, 0x35200000, v68
	global_load_dwordx4 v[40:43], v[40:41], off
	s_nop 0
	global_load_dwordx4 v[44:47], v[44:45], off
	v_addc_co_u32_e32 v49, vcc, 0, v69, vcc
	v_add_co_u32_e32 v52, vcc, 0x35400000, v68
	v_pk_add_f32 v[8:9], v[16:17], v[8:9]
	s_nop 0
	v_addc_co_u32_e32 v53, vcc, 0, v69, vcc
	v_add_co_u32_e32 v56, vcc, 0x35600000, v68
	global_load_dwordx4 v[48:51], v[48:49], off
	s_nop 0
	global_load_dwordx4 v[52:55], v[52:53], off
	v_addc_co_u32_e32 v57, vcc, 0, v69, vcc
	v_add_co_u32_e32 v60, vcc, 0x35800000, v68
	s_waitcnt vmcnt(8)
	v_pk_add_f32 v[10:11], v[22:23], v[10:11]
	v_addc_co_u32_e32 v61, vcc, 0, v69, vcc
	v_add_co_u32_e32 v64, vcc, 0x35a00000, v68
	global_load_dwordx4 v[56:59], v[56:57], off
	s_nop 0
	global_load_dwordx4 v[60:63], v[60:61], off
	v_addc_co_u32_e32 v65, vcc, 0, v69, vcc
	v_add_co_u32_e32 v68, vcc, 0x35c00000, v68
	global_load_dwordx4 v[64:67], v[64:65], off
	s_nop 0
	v_addc_co_u32_e32 v69, vcc, 0, v69, vcc
	global_load_dwordx4 v[68:71], v[68:69], off
	v_pk_add_f32 v[8:9], v[20:21], v[8:9]
	s_waitcnt vmcnt(11)
	v_pk_add_f32 v[10:11], v[26:27], v[10:11]
	v_pk_add_f32 v[8:9], v[24:25], v[8:9]
	s_waitcnt vmcnt(10)
	v_pk_add_f32 v[10:11], v[30:31], v[10:11]
	v_pk_add_f32 v[8:9], v[28:29], v[8:9]
	s_waitcnt vmcnt(9)
	v_pk_add_f32 v[10:11], v[34:35], v[10:11]
	v_pk_add_f32 v[8:9], v[32:33], v[8:9]
	s_waitcnt vmcnt(8)
	v_pk_add_f32 v[10:11], v[38:39], v[10:11]
	v_pk_add_f32 v[8:9], v[36:37], v[8:9]
	s_waitcnt vmcnt(7)
	v_pk_add_f32 v[10:11], v[42:43], v[10:11]
	v_pk_add_f32 v[8:9], v[40:41], v[8:9]
	s_waitcnt vmcnt(6)
	v_pk_add_f32 v[10:11], v[46:47], v[10:11]
	v_pk_add_f32 v[8:9], v[44:45], v[8:9]
	s_waitcnt vmcnt(5)
	v_pk_add_f32 v[10:11], v[50:51], v[10:11]
	v_pk_add_f32 v[8:9], v[48:49], v[8:9]
	s_waitcnt vmcnt(4)
	v_pk_add_f32 v[10:11], v[54:55], v[10:11]
	v_pk_add_f32 v[8:9], v[52:53], v[8:9]
	s_waitcnt vmcnt(3)
	v_pk_add_f32 v[10:11], v[58:59], v[10:11]
	v_pk_add_f32 v[8:9], v[56:57], v[8:9]
	s_waitcnt vmcnt(2)
	v_pk_add_f32 v[10:11], v[62:63], v[10:11]
	v_pk_add_f32 v[8:9], v[60:61], v[8:9]
	s_waitcnt vmcnt(1)
	v_pk_add_f32 v[10:11], v[66:67], v[10:11]
	v_pk_add_f32 v[8:9], v[64:65], v[8:9]
	s_waitcnt vmcnt(0)
	v_pk_add_f32 v[10:11], v[70:71], v[10:11]
	v_pk_add_f32 v[8:9], v[68:69], v[8:9]
	s_nop 0
	v_cvt_pk_bf16_f32 v8, v8, v9
	v_cvt_pk_bf16_f32 v9, v10, v11
	global_store_dwordx2 v[4:5], v[8:9], off
	v_lshl_add_u64 v[4:5], v[4:5], 0, s[56:57]
	s_cbranch_scc1 .LBB0_983
; __device__ __forceinline__ unsigned char* WSP() { return (unsigned char*)IN(41); }
; __device__ __forceinline__ int TID() { int t = threadIdx.x; asm volatile("" : "+v"(t)); return t; }
; __device__ __forceinline__ int BID() { int b = blockIdx.x; asm volatile("" : "+s"(b)); return b; }
; __device__ __forceinline__ int GSZ() { int g = gridDim.x; asm volatile("" : "+s"(g)); return g; }
; __device__ __forceinline__ unsigned pk2(float lo, float hi) { f32x2c v = {lo, hi}; return __builtin_bit_cast(unsigned, __builtin_convertvector(v, bf16x2c)); }
; __device__ __forceinline__ int rfl(int v) { return __builtin_amdgcn_readfirstlane(v); }
; __device__ __forceinline__ void row_post1(const Params& p, int layer) {
;     const int tid_ = TID(), lane = tid_ & 63, wave_ = rfl(tid_ >> 6), bid_ = BID(), gw = bid_ * 8 + wave_, ngw = GSZ() * 8;
;     unsigned char* ws = WSP();
;     bf16_t* X = (bf16_t*)(ws + ((layer & 1) ? WS_XB : WS_XA));
;     const bf16_t* MIX = (const bf16_t*)(ws + WS_MIX);
;     const float* g1 = IN(8) + (size_t)layer * D; const float* g2 = IN(9) + (size_t)layer * D;
;     presum_sample_rows((bf16_t*)(ws + WS_MIX), bid_, tid_);
;     const int nit = (MP - gw + ngw - 1) / ngw;
;     for (int it_ = 0; it_ <= nit; ++it_) {
;         int m = gw + it_ * ngw;
;         if (it_ == nit) { if (wave_ >= 4 || bid_ >= MS / 4) break; m = MP + 4 * bid_ + wave_; }
;         f32x4 x[8], mx[8];
;         xrow_load(X, layer == 0, m, lane, x);
;         row_load_bf16(MIX + (size_t)m * D, lane, mx);
;         const float rs = row_rstd(mx);
; #pragma unroll
;         for (int j = 0; j < 8; ++j) { const f32x4 g = *(const f32x4*)(g1 + 256 * j + 4 * lane); x[j] += mx[j] * rs * g; u32x2 w; w.x = pk2(x[j][0], x[j][1]); w.y = pk2(x[j][2], x[j][3]); *(u32x2*)(X + (size_t)m * D + 256 * j + 4 * lane) = w; }
;         const float rs2 = row_rstd(x);
; #pragma unroll
;         for (int j = 0; j < 8; ++j) { const f32x4 g = *(const f32x4*)(g2 + 256 * j + 4 * lane); x[j] = x[j] * rs2 * g; }
.LBB0_984:
	s_lshl_b32 s5, s5, 3
	s_abs_i32 s15, s5
	v_cvt_f32_u32_e32 v1, s15
	s_ashr_i32 s12, s4, 6
	s_lshl_b32 s4, s14, 3
	s_add_i32 s4, s4, s12
	v_rcp_iflag_f32_e32 v1, v1
	s_sub_i32 s16, s5, s4
	s_add_i32 s17, s16, 0x1fff
	s_sub_i32 s16, 0xffffe001, s16
	v_mul_f32_e32 v1, 0x4f7ffffe, v1
	v_cvt_u32_f32_e32 v1, v1
	s_xor_b32 s13, s17, s5
	s_max_i32 s16, s17, s16
	s_sub_i32 s17, 0, s15
	v_readfirstlane_b32 s18, v1
	s_mul_i32 s17, s17, s18
	s_mul_hi_u32 s17, s18, s17
	s_add_i32 s18, s18, s17
	s_mul_hi_u32 s17, s16, s18
	s_mul_i32 s18, s17, s15
	s_sub_i32 s16, s16, s18
	s_ashr_i32 s13, s13, 31
	s_add_i32 s18, s17, 1
	s_sub_i32 s19, s16, s15
	s_cmp_ge_u32 s16, s15
	s_cselect_b32 s17, s18, s17
	s_cselect_b32 s16, s19, s16
	s_add_i32 s18, s17, 1
	s_cmp_ge_u32 s16, s15
	s_cselect_b32 s15, s18, s17
	s_xor_b32 s15, s15, s13
	s_sub_i32 s16, s15, s13
	s_cmp_lt_i32 s16, 0
	s_waitcnt lgkmcnt(0)
	s_barrier
	s_cbranch_scc1 .LBB0_997
	v_readlane_b32 s16, v234, 26
	s_add_u32 s16, s6, s16
	s_addc_u32 s17, s7, 0
	v_readlane_b32 s20, v234, 52
	v_readlane_b32 s21, v234, 53
	s_add_u32 s18, s2, s20
	s_addc_u32 s19, s3, s21
	s_add_u32 s10, s10, s20
	s_addc_u32 s11, s11, s21
	s_waitcnt vmcnt(0)
	v_and_b32_e32 v4, 0xfc, v0
	s_lshl_b32 s99, 1, s100
	s_cmp_lt_i32 s12, s99
	v_lshlrev_b32_e32 v2, 1, v4
	s_cselect_b64 s[2:3], -1, 0
	v_lshl_add_u64 v[6:7], s[6:7], 0, v[2:3]
	s_mov_b64 s[6:7], 0x10d00000
	s_and_b64 s[2:3], s[2:3], s[8:9]
	s_lshl_b32 s8, s14, s100
	v_lshl_add_u64 v[0:1], s[16:17], 0, v[2:3]
	s_waitcnt vmcnt(0)
	v_lshl_add_u64 v[40:41], v[6:7], 0, s[6:7]
	v_lshlrev_b32_e32 v2, 2, v4
	s_mov_b64 s[6:7], 0xec00000
	s_add_i32 s12, s12, s8
	v_lshl_add_u64 v[42:43], s[18:19], 0, v[2:3]
	v_lshl_add_u64 v[44:45], s[10:11], 0, v[2:3]
	v_lshl_add_u64 v[46:47], v[6:7], 0, s[6:7]
	s_mov_b64 s[6:7], 0x1400
	s_mov_b64 s[8:9], 0x1800
	s_mov_b64 s[10:11], 0x1c00
	s_addk_i32 s12, 0x2000
	v_lshl_add_u64 v[48:49], v[42:43], 0, s[56:57]
	v_lshl_add_u64 v[50:51], v[42:43], 0, s[6:7]
	v_lshl_add_u64 v[52:53], v[42:43], 0, s[8:9]
	v_lshl_add_u64 v[54:55], v[42:43], 0, s[10:11]
	v_lshl_add_u64 v[56:57], v[44:45], 0, s[56:57]
	v_lshl_add_u64 v[58:59], v[44:45], 0, s[6:7]
	v_lshl_add_u64 v[60:61], v[44:45], 0, s[8:9]
	v_lshl_add_u64 v[62:63], v[44:45], 0, s[10:11]
	s_sub_i32 s13, s13, s15
	v_lshlrev_b32_e32 v2, 2, v4
	global_load_dwordx4 v[160:163], v[42:43], off
	global_load_dwordx4 v[164:167], v[42:43], off offset:1024
	global_load_dwordx4 v[168:171], v[42:43], off offset:2048
	global_load_dwordx4 v[172:175], v[42:43], off offset:3072
	global_load_dwordx4 v[176:179], v[48:49], off
	global_load_dwordx4 v[180:183], v[50:51], off
	global_load_dwordx4 v[184:187], v[52:53], off
	global_load_dwordx4 v[188:191], v[54:55], off
	global_load_dwordx4 v[192:195], v[44:45], off
	global_load_dwordx4 v[196:199], v[44:45], off offset:1024
	global_load_dwordx4 v[200:203], v[44:45], off offset:2048
	global_load_dwordx4 v[204:207], v[44:45], off offset:3072
	global_load_dwordx4 v[208:211], v[56:57], off
	global_load_dwordx4 v[212:215], v[58:59], off
	global_load_dwordx4 v[216:219], v[60:61], off
	global_load_dwordx4 v[220:223], v[62:63], off
	s_branch .LBB0_989
